# lever4: one static s_setprio 1 for waves 4-7 in both GEMM phases, all per-segment flips deleted
# baseline (speedup 1.0000x reference)
.LBB0_392:
	s_and_b32 s8, s6, 3
	s_lshl_b32 s81, s7, 6
	s_lshl_b32 s3, s7, 13
	s_lshl_b32 s6, s8, 12
	s_cmpk_gt_u32 s61, 0xff
	s_cselect_b64 s[38:39], -1, 0
	s_add_i32 s4, s50, -11
	s_cmp_gt_u32 s4, 2
	s_cselect_b64 s[40:41], -1, 0
	s_add_i32 m0, s69, 0x18000
	v_lshl_add_u64 v[6:7], v[6:7], 0, s[62:63]
	s_waitcnt vmcnt(2)
	s_barrier
	global_load_lds_dwordx4 v[6:7], off
	v_lshl_add_u64 v[4:5], v[4:5], 0, s[62:63]
	s_add_i32 m0, s69, 0x1a000
	s_add_i32 s96, s69, 0x8000
	s_add_i32 s36, s69, 0xa000
	global_load_lds_dwordx4 v[4:5], off
	v_lshl_add_u64 v[0:1], v[0:1], 0, s[62:63]
	s_mov_b32 m0, s96
	s_add_u32 s4, s12, 0x10080
	global_load_lds_dwordx4 v[0:1], off
	v_lshl_add_u64 v[0:1], v[2:3], 0, s[62:63]
	s_mov_b32 m0, s36
	s_addc_u32 s5, s13, 0
	global_load_lds_dwordx4 v[0:1], off
	s_add_i32 m0, s69, 0x1c000
	v_lshl_add_u64 v[0:1], s[4:5], 0, v[156:157]
	global_load_lds_dwordx4 v[0:1], off
	v_lshl_add_u64 v[0:1], s[4:5], 0, v[160:161]
	s_add_i32 m0, s69, 0x1e000
	v_bfe_u32 v2, v8, 4, 2
	global_load_lds_dwordx4 v[0:1], off
	s_cmpk_lt_u32 s16, 0x100
	v_and_b32_e32 v163, 15, v8
	v_lshlrev_b32_e32 v1, 4, v2
	v_lshlrev_b32_e32 v4, 2, v8
	s_cselect_b64 s[42:43], -1, 0
	s_or_b32 s9, s81, 48
	v_or_b32_e32 v0, s81, v163
	v_lshl_or_b32 v3, v163, 6, v1
	v_and_b32_e32 v162, 32, v4
	v_writelane_b32 v252, s9, 38
	s_and_b32 s9, s16, 0xffffff00
	v_bitop3_b32 v4, v3, s3, v162 bitop3:0xde
	v_bitop3_b32 v221, v3, s6, v162 bitop3:0xde
	s_lshl_b32 s10, s8, 6
	v_lshlrev_b32_e32 v3, 4, v0
	v_or_b32_e32 v0, s9, v163
	v_or3_b32 v0, v0, v1, s10
	v_readlane_b32 s11, v252, 2
	v_ashrrev_i32_e32 v1, 31, v0
	v_lshlrev_b64 v[164:165], 4, v[0:1]
	v_add_u32_e32 v223, s11, v3
	v_readlane_b32 s11, v252, 3
	v_lshlrev_b32_e32 v1, 14, v9
	v_and_b32_e32 v1, 0xffff8000, v1
	v_add_u32_e32 v224, s11, v3
	v_readlane_b32 s11, v252, 4
	v_cmp_eq_u32_e64 s[44:45], 0, v2
	v_lshl_or_b32 v230, v2, 3, s10
	v_add_u32_e32 v225, s11, v3
	v_readlane_b32 s11, v252, 5
	v_lshl_add_u32 v1, v10, 11, v1
	v_and_b32_e32 v2, 1, v9
	v_add_u32_e32 v226, s11, v3
	v_readlane_b32 s11, v252, 6
	v_lshl_or_b32 v1, v2, 6, v1
	s_mov_b32 s3, s91
	v_add_u32_e32 v227, s11, v3
	v_readlane_b32 s11, v252, 7
	s_mul_i32 s4, s61, 0x40800
	s_mov_b32 s5, s91
	v_add_u32_e32 v228, s11, v3
	v_readlane_b32 s11, v252, 8
	v_lshl_add_u32 v166, v11, 1, v1
	v_lshlrev_b32_e32 v1, 14, v12
	s_movk_i32 s9, 0x100
	v_add_u32_e32 v229, s11, v3
	v_readlane_b32 s11, v252, 9
	v_and_b32_e32 v1, 0xffff8000, v1
	s_lshl_b64 s[48:49], s[2:3], 2
	s_lshl_b64 s[2:3], s[4:5], 2
	s_waitcnt vmcnt(6)
	s_lshl_b32 s8, s8, 2
	v_cmp_gt_i32_e64 s[92:93], s9, v0
	v_lshlrev_b32_e32 v5, 4, v0
	v_add_u32_e32 v0, s11, v3
	v_lshl_add_u32 v1, v13, 11, v1
	v_and_b32_e32 v2, 1, v12
	v_writelane_b32 v252, s2, 40
	s_mul_i32 s90, s61, 0x24000
	s_or_b32 s17, s81, 32
	v_lshl_or_b32 v1, v2, 6, v1
	v_add_u32_e32 v232, s8, v0
	v_writelane_b32 v252, s3, 41
	v_add_u32_e32 v0, 0, v5
	s_mov_b32 s51, s50
	v_cmp_gt_u32_e64 s[6:7], 8, v163
	v_and_b32_e32 v222, 7, v8
	s_mov_b32 s37, 0
	s_or_b32 s74, s81, 16
	s_ashr_i32 s9, s25, 31
	s_ashr_i32 s50, s80, 31
	v_mov_b32_e32 v167, v97
	v_lshl_add_u32 v168, v14, 1, v1
	v_mov_b32_e32 v169, v97
	v_add_u32_e32 v231, 0, v4
	s_lshl_b64 s[46:47], s[90:91], 2
	s_mov_b32 s90, s17
	v_add_u32_e32 v233, 0x20000, v0
	v_writelane_b32 v252, s82, 36
	s_barrier
	s_nop 0
	v_writelane_b32 v252, s83, 37
	s_cmp_lg_u32 s81, 0
	s_cbranch_scc0 .Lprio_out_skip
	s_setprio 1
.Lprio_out_skip:
	s_branch .LBB0_395
.LBB0_393:
	s_mov_b64 s[2:3], 0

.LBB0_719:
	s_setprio 0
	s_waitcnt vmcnt(0)
	s_barrier
	s_load_dwordx2 s[48:49], s[0:1], 0xa8
	s_mov_b32 s68, 0xc2800000
	s_mov_b32 s70, 0xc2840000
	v_readlane_b32 s46, v252, 16
	v_readlane_b32 s47, v252, 17
	s_mov_b32 s50, s51
	s_waitcnt lgkmcnt(0)
	v_readlane_b32 s49, v252, 18
	s_mov_b32 s51, 0x27c00000
	s_movk_i32 s53, 0x1000
	s_mov_b32 s54, 0x18000
	s_movk_i32 s55, 0x90
	s_movk_i32 s56, 0xc0
	s_mov_b32 s57, 0xc2fc0000
	s_mov_b32 s69, 0xc2820000
	s_mov_b32 s71, 0xc2860000
	s_movk_i32 s58, 0x2000
	s_mov_b32 s60, 0x78000
	s_mov_b32 s65, 0x12000
	s_mov_b32 s66, 0x14000
	s_mov_b32 s74, 0x16000
	s_movk_i32 s76, 0x4000
	s_movk_i32 s78, 0x6000
	s_mov_b32 s79, 0x24000
	s_mov_b32 s84, 0x1a000
	s_mov_b32 s85, 0x8000
	s_mov_b32 s86, 0xa000
	s_mov_b32 s87, 0x1c000
	s_mov_b32 s88, 0x1e000
	s_mov_b32 s92, 0x20000
	s_mov_b32 s93, 0xc000
	s_mov_b32 s96, 0xe000
	s_mov_b32 s35, 0x2aaaaaab
	s_mov_b32 s38, 0x30000

.LBB0_733:
	s_and_b32 s3, s6, 3
	s_waitcnt lgkmcnt(0)
	s_bfe_u32 s16, s61, 0x70001
	s_add_i32 m0, s79, 0x18000
	v_lshl_add_u64 v[6:7], v[6:7], 0, s[62:63]
	s_lshl_b32 s20, s7, 6
	s_lshl_b32 s7, s7, 13
	s_lshl_b32 s14, s3, 12
	s_and_b32 s15, s61, 0xff
	s_lshl_b32 s17, s16, 20
	s_lshl_b32 s18, s16, 19
	s_waitcnt vmcnt(2)
	s_barrier
	global_load_lds_dwordx4 v[6:7], off
	v_lshl_add_u64 v[4:5], v[4:5], 0, s[62:63]
	s_add_i32 m0, s79, 0x1a000
	s_add_i32 s21, s79, 0x8000
	s_add_i32 s61, s79, 0xa000
	global_load_lds_dwordx4 v[4:5], off
	v_lshl_add_u64 v[2:3], v[2:3], 0, s[62:63]
	s_mov_b32 m0, s21
	s_add_u32 s8, s12, 0x10080
	global_load_lds_dwordx4 v[2:3], off
	v_lshl_add_u64 v[2:3], v[8:9], 0, s[62:63]
	s_mov_b32 m0, s61
	s_addc_u32 s9, s13, 0
	global_load_lds_dwordx4 v[2:3], off
	s_add_i32 m0, s79, 0x1c000
	v_lshl_add_u64 v[2:3], s[8:9], 0, v[156:157]
	global_load_lds_dwordx4 v[2:3], off
	v_lshl_add_u64 v[2:3], s[8:9], 0, v[160:161]
	s_add_i32 m0, s79, 0x1e000
	v_and_b32_e32 v163, 15, v0
	global_load_lds_dwordx4 v[2:3], off
	v_bfe_u32 v3, v0, 4, 2
	v_lshlrev_b32_e32 v2, 4, v3
	v_lshlrev_b32_e32 v6, 2, v0
	v_lshl_or_b32 v2, v163, 6, v2
	v_and_b32_e32 v162, 32, v6
	v_bitop3_b32 v7, v2, s7, v162 bitop3:0xde
	s_mul_i32 s7, s15, 0x90000
	v_writelane_b32 v252, s7, 35
	s_mul_i32 s7, s16, 0x1e0000
	v_writelane_b32 v252, s7, 26
	s_mul_i32 s7, s16, 0xf0000
	s_cmp_lt_i32 s6, 4
	v_bitop3_b32 v165, v2, s14, v162 bitop3:0xde
	s_mul_i32 s90, s15, 0x10200
	s_mul_i32 s8, s15, 0x24000
	v_writelane_b32 v252, s7, 36
	s_cselect_b64 s[14:15], -1, 0
	v_writelane_b32 v252, s14, 38
	s_cmp_eq_u32 s6, 4
	s_cselect_b64 s[6:7], -1, 0
	v_writelane_b32 v252, s15, 39
	v_writelane_b32 v252, s6, 40
	s_cmpk_lt_u32 s11, 0x100
	v_lshlrev_b32_e32 v5, 3, v3
	v_writelane_b32 v252, s7, 41
	s_cselect_b64 s[6:7], -1, 0
	s_lshl_b32 s96, s10, 3
	v_lshlrev_b32_e32 v209, 5, v3
	v_cvt_f32_ubyte0_e32 v3, s96
	v_rcp_iflag_f32_e32 v3, v3
	v_writelane_b32 v252, s6, 30
	v_and_b32_e32 v207, 7, v0
	v_lshl_add_u64 v[0:1], v[0:1], 0, s[90:91]
	v_mul_f32_e32 v3, 0x4f7ffffe, v3
	v_writelane_b32 v252, s7, 31
	s_add_i32 s9, s20, 0x80
	v_cvt_u32_f32_e32 v3, v3
	v_lshlrev_b64 v[166:167], 4, v[0:1]
	v_lshlrev_b32_e32 v0, 14, v10
	v_lshl_or_b32 v206, s3, 6, v5
	v_writelane_b32 v252, s9, 24
	s_lshl_b32 s3, s3, 8
	v_and_b32_e32 v0, 0xffff8000, v0
	v_writelane_b32 v252, s3, 42
	s_ashr_i32 s3, s25, 31
	v_lshl_add_u32 v0, v11, 11, v0
	v_and_b32_e32 v1, 1, v10
	v_writelane_b32 v252, s3, 22
	s_and_b32 s9, s28, 4
	v_lshl_or_b32 v0, v1, 6, v0
	v_writelane_b32 v252, s9, 43
	s_sub_i32 s9, 0, s96
	v_readfirstlane_b32 s10, v3
	v_lshl_add_u32 v168, v12, 1, v0
	v_lshlrev_b32_e32 v0, 14, v13
	s_lshr_b32 s3, s28, 3
	s_mul_i32 s9, s9, s10
	v_and_b32_e32 v0, 0xffff8000, v0
	s_waitcnt vmcnt(6)
	v_writelane_b32 v252, s3, 44
	s_add_i32 s3, s3, 1
	s_mul_hi_u32 s9, s10, s9
	v_lshl_add_u32 v0, v14, 11, v0
	v_and_b32_e32 v1, 1, v13
	v_or_b32_e32 v4, s20, v163
	v_and_b32_e32 v2, 0xfc, v6
	v_writelane_b32 v252, s3, 45
	s_add_i32 s9, s10, s9
	v_lshl_or_b32 v0, v1, 6, v0
	v_cmp_gt_u32_e64 s[6:7], 8, v163
	v_lshlrev_b32_e32 v208, 4, v4
	v_lshlrev_b32_e32 v164, 8, v163
	s_ashr_i32 s68, s80, 31
	s_mov_b32 s31, s91
	s_mov_b32 s29, s91
	s_mov_b32 s3, 0
	v_writelane_b32 v252, s9, 46
	v_mov_b32_e32 v169, v97
	v_lshl_add_u32 v170, v15, 1, v0
	v_mov_b32_e32 v171, v97
	s_lshl_b32 s8, s8, 2
	v_lshlrev_b32_e32 v180, 2, v2
	v_add_u32_e32 v221, 0, v7
	s_lshl_b32 s58, s17, 2
	s_lshl_b32 s60, s18, 2
	s_movk_i32 s86, 0x77f
	s_barrier
	v_writelane_b32 v252, s8, 47
	s_cmp_lg_u32 s20, 0
	s_cbranch_scc0 .Lprio_in_skip
	s_setprio 1
.Lprio_in_skip:
	s_branch .LBB0_736
.LBB0_734:
	s_mov_b64 s[2:3], 0

.LBB0_1428:
	s_setprio 0
	s_waitcnt vmcnt(0)
	s_barrier
	s_load_dwordx2 s[48:49], s[0:1], 0xa8
	s_mov_b32 s68, 0xc2800000
	s_mov_b32 s70, 0xc2840000
	v_readlane_b32 s46, v252, 16
	v_readlane_b32 s47, v252, 17
	v_readlane_b32 s50, v252, 32
	s_waitcnt lgkmcnt(0)
	v_readlane_b32 s49, v252, 18
	s_mov_b32 s51, 0x27c00000
	s_movk_i32 s53, 0x1000
	s_mov_b32 s54, 0x18000
	s_movk_i32 s55, 0x90
	s_movk_i32 s56, 0xc0
	s_mov_b32 s57, 0xc2fc0000
	s_mov_b32 s69, 0xc2820000
	s_mov_b32 s71, 0xc2860000
	s_movk_i32 s58, 0x2000
	s_mov_b32 s60, 0x78000
	s_mov_b32 s65, 0x12000
	s_mov_b32 s66, 0x14000
	s_mov_b32 s74, 0x16000
	s_movk_i32 s76, 0x4000
	s_movk_i32 s78, 0x6000
	s_mov_b32 s79, 0x24000
	s_mov_b32 s84, 0x1a000
	s_mov_b32 s85, 0x8000
	s_mov_b32 s86, 0xa000
	s_mov_b32 s87, 0x1c000
	s_mov_b32 s88, 0x1e000
	s_mov_b32 s92, 0x20000
	s_mov_b32 s93, 0xc000
	s_mov_b32 s96, 0xe000
	s_branch .LBB0_1476
